# v83 + p9_wspec + p9_trim: drop dead per-tile VALU in attention loops (canonicalising max pair, stale m movs, l fmac+mov->fma)
# speedup vs baseline: 1.0264x; 1.0033x over previous
; #define LAS __attribute__((address_space(3)))
; DI float shfl_xor_l(float v, int lane, int m) { return __int_as_float(__builtin_amdgcn_ds_bpermute((lane ^ m) << 2, __float_as_int(v))); }
; #define A_LOAD(kt) do { const size_t ko = (size_t)(kt) * 64; st0 = *(const u32x4*)(kn_src + ko * 2048); st1 = *(const u32x4*)(kn_src + (ko + 32) * 2048); \
;         st2 = *(const u32x4*)(kr_src + ko * 64); st3 = *(const u32x4*)(v_src + ko); st4 = *(const u32x4*)(v_src + ko + (size_t)64 * 8192); } while (0)
; #define VLD(dst, j, dt) do { LAS unsigned char* va_ = vb + (32 * (dt) + n) * VROW + (16 * (j) + 4 * g) * 2; const u32x2 lo_ = *(const LAS u32x2*)(va_), hi_ = *(const LAS u32x2*)(va_ + 16); dst = (u32x4){lo_.x, lo_.y, hi_.x, hi_.y}; } while (0)
; DI void attn_unit(LAS unsigned char* lds, int wid, int b, int h, int qb) {
;     ...
;     for (int kt = 0; kt < nkt; ++kt) {
;         const int buf = kt & 1;
;         if (kt + 1 < nkt) A_LOAD(kt + 1);
;         if (kt <= cq) {
;             LAS unsigned char* kb = lds + buf * ABUF; LAS unsigned char* vb = kb + KBYTES;
;             f32x16 s0, s1;
; #pragma unroll
;             for (int i = 0; i < 16; ++i) { s0[i] = 0.f; s1[i] = 0.f; }
;     ...
;             bf16x8 ka[3][2];
;             ka[0][0] = KLD(0, 0); ka[0][1] = KLD(0, 1); ka[1][0] = KLD(1, 0); ka[1][1] = KLD(1, 1);
; #pragma unroll
;             for (int ks = 0; ks < 12; ++ks) {
;                 if (ks + 2 < 12) { ka[(ks + 2) % 3][0] = KLD(ks + 2, 0); ka[(ks + 2) % 3][1] = KLD(ks + 2, 1); }
;                 s0 = __builtin_amdgcn_mfma_f32_32x32x16_bf16(ka[ks % 3][0], qf[ks], s0, 0, 0, 0); s1 = __builtin_amdgcn_mfma_f32_32x32x16_bf16(ka[ks % 3][1], qf[ks], s1, 0, 0, 0);
;                 __builtin_amdgcn_sched_barrier(0); }
;             u32x4 vf[2][4];
; #pragma unroll
;             for (int dt = 0; dt < 4; ++dt) VLD(vf[0][dt], 0, dt);
;             float mx = s0[0];
; #pragma unroll
;             for (int i = 1; i < 16; ++i) mx = fmaxf(mx, s0[i]);
; #pragma unroll
;             for (int i = 0; i < 16; ++i) mx = fmaxf(mx, s1[i]);
;             mx = fmaxf(mx, shfl_xor_l(mx, lane, 32));
;             const float mnew = fmaxf(mrow, mx), alpha = __builtin_amdgcn_exp2f(mrow - mnew); mrow = mnew;
.LBB0_1079:
	s_and_b32 s65, s64, 1
	global_load_dwordx4 v[146:149], v194, s[70:71]
	global_load_dwordx4 v[150:153], v194, s[72:73]
	global_load_dwordx4 v[154:157], v192, s[78:79]
	global_load_dwordx4 v[158:161], v190, s[74:75] offset:128
	global_load_dwordx4 v[162:165], v190, s[76:77] offset:128
	s_cmp_gt_u32 s64, s62
	s_cbranch_scc1 .LBB0_1083
	s_mul_i32 s66, s65, 0xa800
	s_add_i32 s66, s66, 0
	v_add3_u32 v171, s66, v199, v202
	ds_read_b128 v[66:69], v171
	ds_read_b128 v[166:169], v171 offset:32
	ds_read_b128 v[82:85], v171 offset:12800
	ds_read_b128 v[172:175], v171 offset:64
	ds_read_b128 v[176:179], v171 offset:12832
	ds_read_b128 v[204:207], v171 offset:12864
	s_waitcnt lgkmcnt(3)
	v_mfma_f32_32x32x16_bf16 v[82:97], v[82:85], v[142:145], v[216:231]
	v_mfma_f32_32x32x16_bf16 v[66:81], v[66:69], v[142:145], v[216:231]
	v_mfma_f32_32x32x16_bf16 v[66:81], v[166:169], v[138:141], v[66:81]
	ds_read_b128 v[166:169], v171 offset:96
	ds_read_b128 v[208:211], v171 offset:12896
	s_waitcnt lgkmcnt(3)
	v_mfma_f32_32x32x16_bf16 v[82:97], v[176:179], v[138:141], v[82:97]
	v_mfma_f32_32x32x16_bf16 v[66:81], v[172:175], v[134:137], v[66:81]
	ds_read_b128 v[172:175], v171 offset:128
	ds_read_b128 v[176:179], v171 offset:12928
	s_waitcnt lgkmcnt(4)
	v_mfma_f32_32x32x16_bf16 v[82:97], v[204:207], v[134:137], v[82:97]
	s_waitcnt lgkmcnt(3)
	v_mfma_f32_32x32x16_bf16 v[66:81], v[166:169], v[130:133], v[66:81]
	ds_read_b128 v[166:169], v171 offset:160
	ds_read_b128 v[204:207], v171 offset:12960
	s_waitcnt lgkmcnt(4)
	v_mfma_f32_32x32x16_bf16 v[82:97], v[208:211], v[130:133], v[82:97]
	s_waitcnt lgkmcnt(3)
	v_mfma_f32_32x32x16_bf16 v[66:81], v[172:175], v[126:129], v[66:81]
	ds_read_b128 v[172:175], v171 offset:192
	ds_read_b128 v[208:211], v171 offset:12992
	s_waitcnt lgkmcnt(4)
	v_mfma_f32_32x32x16_bf16 v[82:97], v[176:179], v[126:129], v[82:97]
	s_waitcnt lgkmcnt(3)
	v_mfma_f32_32x32x16_bf16 v[66:81], v[166:169], v[122:125], v[66:81]
	ds_read_b128 v[166:169], v171 offset:224
	ds_read_b128 v[176:179], v171 offset:13024
	s_waitcnt lgkmcnt(4)
	v_mfma_f32_32x32x16_bf16 v[82:97], v[204:207], v[122:125], v[82:97]
	s_waitcnt lgkmcnt(3)
	v_mfma_f32_32x32x16_bf16 v[66:81], v[172:175], v[118:121], v[66:81]
	ds_read_b128 v[172:175], v171 offset:256
	ds_read_b128 v[204:207], v171 offset:13056
	s_waitcnt lgkmcnt(4)
	v_mfma_f32_32x32x16_bf16 v[82:97], v[208:211], v[118:121], v[82:97]
	s_waitcnt lgkmcnt(3)
	v_mfma_f32_32x32x16_bf16 v[66:81], v[166:169], v[114:117], v[66:81]
	ds_read_b128 v[166:169], v171 offset:288
	ds_read_b128 v[208:211], v171 offset:13088
	s_waitcnt lgkmcnt(4)
	v_mfma_f32_32x32x16_bf16 v[82:97], v[176:179], v[114:117], v[82:97]
	s_waitcnt lgkmcnt(3)
	v_mfma_f32_32x32x16_bf16 v[66:81], v[172:175], v[110:113], v[66:81]
	ds_read_b128 v[172:175], v171 offset:320
	ds_read_b128 v[176:179], v171 offset:13120
	s_waitcnt lgkmcnt(4)
	v_mfma_f32_32x32x16_bf16 v[82:97], v[204:207], v[110:113], v[82:97]
	s_waitcnt lgkmcnt(3)
	v_mfma_f32_32x32x16_bf16 v[66:81], v[166:169], v[106:109], v[66:81]
	ds_read_b128 v[166:169], v171 offset:352
	ds_read_b128 v[212:215], v171 offset:13152
	s_waitcnt lgkmcnt(4)
	v_mfma_f32_32x32x16_bf16 v[82:97], v[208:211], v[106:109], v[82:97]
	s_waitcnt lgkmcnt(3)
	v_mfma_f32_32x32x16_bf16 v[66:81], v[172:175], v[102:105], v[66:81]
	s_waitcnt lgkmcnt(2)
	v_mfma_f32_32x32x16_bf16 v[82:97], v[176:179], v[102:105], v[82:97]
	s_waitcnt lgkmcnt(1)
	v_mfma_f32_32x32x16_bf16 v[66:81], v[166:169], v[98:101], v[66:81]
	v_add_u32_e32 v171, s66, v184
	v_add_u32_e32 v171, v171, v189
	v_add_u32_e32 v204, 0x6000, v171
	v_add_u32_e32 v205, 0x7000, v171
	v_add_u32_e32 v206, 0x8000, v171
	v_add_u32_e32 v207, 0x9000, v171
	ds_read2_b64 v[166:169], v204 offset0:128 offset1:130
	s_nop 4
	v_max_f32_e32 v172, v66, v67
	s_waitcnt lgkmcnt(1)
	v_mfma_f32_32x32x16_bf16 v[82:97], v[212:215], v[98:101], v[82:97]
	v_max3_f32 v172, v172, v68, v69
	v_max3_f32 v172, v172, v70, v71
	v_max3_f32 v172, v172, v72, v73
	v_max3_f32 v172, v172, v74, v75
	v_max3_f32 v172, v172, v76, v77
	v_max3_f32 v172, v172, v78, v79
	v_max3_f32 v172, v172, v80, v81
	s_nop 4
	v_max3_f32 v172, v172, v82, v83
	v_max3_f32 v172, v172, v84, v85
	v_max3_f32 v172, v172, v86, v87
	v_max3_f32 v172, v172, v88, v89
	v_max3_f32 v172, v172, v90, v91
	v_max3_f32 v172, v172, v92, v93
	v_max3_f32 v172, v172, v94, v95
	v_max3_f32 v172, v172, v96, v97
	ds_bpermute_b32 v173, v185, v172
	ds_read2_b64 v[178:181], v205 offset0:160 offset1:162
	ds_read2_b64 v[174:177], v206 offset0:192 offset1:194
	s_waitcnt lgkmcnt(2)
	v_max_f32_e32 v237, v172, v173
	v_cmp_lt_f32_e32 vcc, 0x41000000, v237
	ds_read2_b64 v[170:173], v207 offset0:224 offset1:226
	s_cmp_eq_u32 s64, 0
	s_cbranch_scc1 .Lfold_0_upd
	s_cbranch_vccz .Lfold_0_keep

; DI void attn_unit(LAS unsigned char* lds, int wid, int b, int h, int qb) {
;     ...
;             const float mnew = fmaxf(mrow, mx), alpha = __builtin_amdgcn_exp2f(mrow - mnew); mrow = mnew;
;             float ls = 0.f;
; #pragma unroll
;             for (int i = 0; i < 16; ++i) { s0[i] = __builtin_amdgcn_exp2f(s0[i] - mnew); s1[i] = __builtin_amdgcn_exp2f(s1[i] - mnew); ls += s0[i] + s1[i]; }
.LBB0_1082:
	v_exp_f32_e32 v66, v66
	v_exp_f32_e32 v82, v82
	v_exp_f32_e32 v67, v67
	v_exp_f32_e32 v83, v83
	v_exp_f32_e32 v68, v68
	v_exp_f32_e32 v84, v84
	v_exp_f32_e32 v69, v69
	v_exp_f32_e32 v85, v85
	v_add_f32_e32 v208, v82, v66
	v_exp_f32_e32 v70, v70
	v_exp_f32_e32 v86, v86

; DI unsigned pk2(float a, float b) { f32x2 f = {a, b}; bf16v2 r = __builtin_convertvector(f, bf16v2); return __builtin_bit_cast(unsigned, r); }
; #define VLD(dst, j, dt) do { LAS unsigned char* va_ = vb + (32 * (dt) + n) * VROW + (16 * (j) + 4 * g) * 2; const u32x2 lo_ = *(const LAS u32x2*)(va_), hi_ = *(const LAS u32x2*)(va_ + 16); dst = (u32x4){lo_.x, lo_.y, hi_.x, hi_.y}; } while (0)
; DI void attn_unit(LAS unsigned char* lds, int wid, int b, int h, int qb) {
;     ...
;             for (int i = 0; i < 16; ++i) { s0[i] = __builtin_amdgcn_exp2f(s0[i] - mnew); s1[i] = __builtin_amdgcn_exp2f(s1[i] - mnew); ls += s0[i] + s1[i]; }
;             lrow = lrow * alpha + ls;
;             if (__builtin_amdgcn_ballot_w64(alpha != 1.f) != 0ull) {
; #pragma unroll
;                 for (int dt = 0; dt < 4; ++dt)
; #pragma unroll
;                     for (int i = 0; i < 16; ++i) o[dt][i] *= alpha;
;             }
;             bf16x8 pf[4];
; #pragma unroll
;             for (int jj = 0; jj < 2; ++jj) { u32x4 w0, w1;
;                 w0.x = pk2(s0[8 * jj + 0], s0[8 * jj + 1]); w0.y = pk2(s0[8 * jj + 2], s0[8 * jj + 3]); w0.z = pk2(s0[8 * jj + 4], s0[8 * jj + 5]); w0.w = pk2(s0[8 * jj + 6], s0[8 * jj + 7]);
;                 w1.x = pk2(s1[8 * jj + 0], s1[8 * jj + 1]); w1.y = pk2(s1[8 * jj + 2], s1[8 * jj + 3]); w1.z = pk2(s1[8 * jj + 4], s1[8 * jj + 5]); w1.w = pk2(s1[8 * jj + 6], s1[8 * jj + 7]);
;                 pf[jj] = __builtin_bit_cast(bf16x8, w0); pf[2 + jj] = __builtin_bit_cast(bf16x8, w1); }
; #pragma unroll
;             for (int j = 0; j < 4; ++j) {
;                 if (j < 3) {
; #pragma unroll
;                     for (int dt = 0; dt < 4; ++dt) VLD(vf[(j + 1) & 1][dt], j + 1, dt);
;                 }
; #pragma unroll
;                 for (int dt = 0; dt < 4; ++dt) o[dt] = __builtin_amdgcn_mfma_f32_32x32x16_bf16(__builtin_bit_cast(bf16x8, vf[j & 1][dt]), pf[j], o[dt], 0, 0, 0);
;                 __builtin_amdgcn_sched_barrier(0); }
;     ...
;         }
;         if (kt + 1 < nkt) A_WRITE(buf ^ 1);
	v_add_f32_e32 v209, v83, v67
	v_exp_f32_e32 v71, v71
	v_exp_f32_e32 v87, v87
	v_add_f32_e32 v208, v209, v208
	v_add_f32_e32 v209, v84, v68
	v_exp_f32_e32 v72, v72
	v_exp_f32_e32 v88, v88
	v_add_f32_e32 v208, v209, v208
	v_add_f32_e32 v209, v85, v69
	v_exp_f32_e32 v73, v73
	v_exp_f32_e32 v89, v89
	v_add_f32_e32 v208, v209, v208
	v_add_f32_e32 v209, v86, v70
	v_exp_f32_e32 v74, v74
	v_exp_f32_e32 v90, v90
	v_add_f32_e32 v208, v209, v208
	v_add_f32_e32 v209, v87, v71
	v_exp_f32_e32 v75, v75
	v_exp_f32_e32 v91, v91
	v_add_f32_e32 v208, v209, v208
	v_add_f32_e32 v209, v88, v72
	v_exp_f32_e32 v76, v76
	v_exp_f32_e32 v92, v92
	v_add_f32_e32 v208, v209, v208
	v_add_f32_e32 v209, v89, v73
	v_exp_f32_e32 v77, v77
	v_exp_f32_e32 v93, v93
	v_add_f32_e32 v208, v209, v208
	v_add_f32_e32 v209, v90, v74
	v_exp_f32_e32 v78, v78
	v_exp_f32_e32 v94, v94
	v_add_f32_e32 v208, v209, v208
	v_add_f32_e32 v209, v91, v75
	v_exp_f32_e32 v79, v79
	v_exp_f32_e32 v95, v95
	v_add_f32_e32 v208, v209, v208
	v_add_f32_e32 v209, v92, v76
	v_exp_f32_e32 v80, v80
	v_exp_f32_e32 v96, v96
	v_add_f32_e32 v208, v209, v208
	v_add_f32_e32 v209, v93, v77
	v_exp_f32_e32 v81, v81
	v_exp_f32_e32 v97, v97
	v_add_f32_e32 v208, v209, v208
	v_add_f32_e32 v209, v94, v78
	v_add_f32_e32 v208, v209, v208
	v_add_f32_e32 v209, v95, v79
	v_add_f32_e32 v208, v209, v208
	v_cvt_pk_bf16_f32 v66, v66, v67
	v_cvt_pk_bf16_f32 v67, v68, v69
	v_cvt_pk_bf16_f32 v68, v70, v71
	v_cvt_pk_bf16_f32 v69, v72, v73
	v_add_f32_e32 v70, v96, v80
	v_add_f32_e32 v70, v70, v208
	v_mfma_f32_32x32x16_bf16 v[50:65], v[166:169], v[66:69], v[50:65]
	v_add_f32_e32 v71, v97, v81
	v_add_f32_e32 v166, v71, v70
	v_cvt_pk_bf16_f32 v70, v82, v83
	v_cvt_pk_bf16_f32 v71, v84, v85
	v_cvt_pk_bf16_f32 v72, v86, v87
	v_cvt_pk_bf16_f32 v73, v88, v89
	v_cvt_pk_bf16_f32 v74, v74, v75
	s_waitcnt lgkmcnt(2)
	v_mfma_f32_32x32x16_bf16 v[34:49], v[178:181], v[66:69], v[34:49]
	v_cvt_pk_bf16_f32 v75, v76, v77
	v_cvt_pk_bf16_f32 v76, v78, v79
	v_cvt_pk_bf16_f32 v77, v80, v81
	v_cvt_pk_bf16_f32 v78, v90, v91
	v_cvt_pk_bf16_f32 v79, v92, v93
	v_cvt_pk_bf16_f32 v80, v94, v95
	v_cvt_pk_bf16_f32 v81, v96, v97
	s_waitcnt lgkmcnt(1)
	v_mfma_f32_32x32x16_bf16 v[18:33], v[174:177], v[66:69], v[18:33]
	ds_read2_b64 v[82:85], v204 offset0:132 offset1:134
	ds_read2_b64 v[86:89], v205 offset0:164 offset1:166
	ds_read2_b64 v[90:93], v206 offset0:196 offset1:198
	ds_read2_b64 v[94:97], v207 offset0:228 offset1:230
	v_fma_f32 v187, v187, v196, v166
	s_waitcnt lgkmcnt(4)
	v_mfma_f32_32x32x16_bf16 v[2:17], v[170:173], v[66:69], v[2:17]
	s_waitcnt lgkmcnt(3)
	v_mfma_f32_32x32x16_bf16 v[50:65], v[82:85], v[74:77], v[50:65]
	s_waitcnt lgkmcnt(2)
	v_mfma_f32_32x32x16_bf16 v[34:49], v[86:89], v[74:77], v[34:49]
	s_waitcnt lgkmcnt(1)
	v_mfma_f32_32x32x16_bf16 v[18:33], v[90:93], v[74:77], v[18:33]
	ds_read2_b64 v[66:69], v204 offset0:136 offset1:138
	ds_read2_b64 v[82:85], v205 offset0:168 offset1:170
	ds_read2_b64 v[86:89], v206 offset0:200 offset1:202
	ds_read2_b64 v[90:93], v207 offset0:232 offset1:234
	s_waitcnt lgkmcnt(4)
	v_mfma_f32_32x32x16_bf16 v[2:17], v[94:97], v[74:77], v[2:17]
	s_waitcnt lgkmcnt(3)
	v_mfma_f32_32x32x16_bf16 v[50:65], v[66:69], v[70:73], v[50:65]
	s_waitcnt lgkmcnt(2)
	v_mfma_f32_32x32x16_bf16 v[34:49], v[82:85], v[70:73], v[34:49]
	s_waitcnt lgkmcnt(1)
	v_mfma_f32_32x32x16_bf16 v[18:33], v[86:89], v[70:73], v[18:33]
	ds_read2_b64 v[66:69], v204 offset0:140 offset1:142
	ds_read2_b64 v[74:77], v205 offset0:172 offset1:174
	ds_read2_b64 v[82:85], v206 offset0:204 offset1:206
	ds_read2_b64 v[86:89], v207 offset0:236 offset1:238
	s_waitcnt lgkmcnt(4)
	v_mfma_f32_32x32x16_bf16 v[2:17], v[90:93], v[70:73], v[2:17]
	s_waitcnt lgkmcnt(3)
	v_mfma_f32_32x32x16_bf16 v[50:65], v[66:69], v[78:81], v[50:65]
	s_waitcnt lgkmcnt(2)
	v_mfma_f32_32x32x16_bf16 v[34:49], v[74:77], v[78:81], v[34:49]
	s_waitcnt lgkmcnt(1)
	v_mfma_f32_32x32x16_bf16 v[18:33], v[82:85], v[78:81], v[18:33]
	s_waitcnt lgkmcnt(0)
	v_mfma_f32_32x32x16_bf16 v[2:17], v[86:89], v[78:81], v[2:17]
	s_branch .LBB0_1084
.LBB0_1083:
.LBB0_1084:
	s_add_u32 s70, s70, 0x40000
	s_addc_u32 s71, s71, 0
	s_add_u32 s72, s72, 0x40000
	s_addc_u32 s73, s73, 0
	s_add_u32 s78, s78, 0x2000
	s_addc_u32 s79, s79, 0
	s_add_u32 s74, s74, 0x80
	s_addc_u32 s75, s75, 0
	s_add_u32 s76, s76, 0x80
	s_addc_u32 s77, s77, 0
	s_add_i32 s64, s64, 1
	s_cmp_lg_u32 s65, 0
	s_cbranch_scc1 .Lw1_b0
	s_waitcnt vmcnt(4)
	ds_write_b128 v186, v[146:149] offset:43008
	s_waitcnt vmcnt(3)
	ds_write_b128 v186, v[150:153] offset:55808
	s_waitcnt vmcnt(2)
	ds_write_b128 v188, v[154:157] offset:43264
	s_waitcnt vmcnt(1)
	ds_write2_b64 v240, v[158:159], v[160:161] offset1:1
	s_waitcnt vmcnt(0)
	ds_write2_b64 v241, v[162:163], v[164:165] offset1:1
	s_branch .Lw1_join

; #define LAS __attribute__((address_space(3)))
; DI float shfl_xor_l(float v, int lane, int m) { return __int_as_float(__builtin_amdgcn_ds_bpermute((lane ^ m) << 2, __float_as_int(v))); }
; #define VLD(dst, j, dt) do { LAS unsigned char* va_ = vb + (32 * (dt) + n) * VROW + (16 * (j) + 4 * g) * 2; const u32x2 lo_ = *(const LAS u32x2*)(va_), hi_ = *(const LAS u32x2*)(va_ + 16); dst = (u32x4){lo_.x, lo_.y, hi_.x, hi_.y}; } while (0)
; DI void attn_unit(LAS unsigned char* lds, int wid, int b, int h, int qb) {
;     ...
;         if (kt <= cq) {
;             LAS unsigned char* kb = lds + buf * ABUF; LAS unsigned char* vb = kb + KBYTES;
;             f32x16 s0, s1;
; #pragma unroll
;             for (int i = 0; i < 16; ++i) { s0[i] = 0.f; s1[i] = 0.f; }
;     ...
;             bf16x8 ka[3][2];
;             ka[0][0] = KLD(0, 0); ka[0][1] = KLD(0, 1); ka[1][0] = KLD(1, 0); ka[1][1] = KLD(1, 1);
; #pragma unroll
;             for (int ks = 0; ks < 12; ++ks) {
;                 if (ks + 2 < 12) { ka[(ks + 2) % 3][0] = KLD(ks + 2, 0); ka[(ks + 2) % 3][1] = KLD(ks + 2, 1); }
;                 s0 = __builtin_amdgcn_mfma_f32_32x32x16_bf16(ka[ks % 3][0], qf[ks], s0, 0, 0, 0); s1 = __builtin_amdgcn_mfma_f32_32x32x16_bf16(ka[ks % 3][1], qf[ks], s1, 0, 0, 0);
;                 __builtin_amdgcn_sched_barrier(0); }
;             u32x4 vf[2][4];
; #pragma unroll
;             for (int dt = 0; dt < 4; ++dt) VLD(vf[0][dt], 0, dt);
;             float mx = s0[0];
; #pragma unroll
;             for (int i = 1; i < 16; ++i) mx = fmaxf(mx, s0[i]);
; #pragma unroll
;             for (int i = 0; i < 16; ++i) mx = fmaxf(mx, s1[i]);
;             mx = fmaxf(mx, shfl_xor_l(mx, lane, 32));
;             const float mnew = fmaxf(mrow, mx), alpha = __builtin_amdgcn_exp2f(mrow - mnew); mrow = mnew;
;     ...
;         if (kt + 1 < nkt) A_WRITE(buf ^ 1);
;         __syncthreads();
.Lw1_join:
	s_cmp_eq_u32 s63, s64
	s_waitcnt lgkmcnt(0)
	s_barrier
	s_cbranch_scc1 .LBB0_1086
	s_branch .LBB0_1079
.LBB0_1086:
	s_or_b32 s61, s61, 2
	s_cmp_ge_u32 s61, s62
	s_cbranch_scc1 .LBB0_1090
	s_bitcmp1_b32 s63, 0
	s_cselect_b32 s61, 0xa800, 0
	s_add_i32 s61, s61, 0
	v_add3_u32 v162, s61, v199, v202
	ds_read_b128 v[66:69], v162
	ds_read_b128 v[146:149], v162 offset:32
	ds_read_b128 v[82:85], v162 offset:12800
	ds_read_b128 v[150:153], v162 offset:64
	ds_read_b128 v[154:157], v162 offset:12832
	ds_read_b128 v[158:161], v162 offset:12864
	s_waitcnt lgkmcnt(3)
	v_mfma_f32_32x32x16_bf16 v[82:97], v[82:85], v[142:145], v[216:231]
	v_mfma_f32_32x32x16_bf16 v[66:81], v[66:69], v[142:145], v[216:231]
	v_mfma_f32_32x32x16_bf16 v[66:81], v[146:149], v[138:141], v[66:81]
	ds_read_b128 v[142:145], v162 offset:96
	ds_read_b128 v[146:149], v162 offset:12896
	s_waitcnt lgkmcnt(3)
	v_mfma_f32_32x32x16_bf16 v[82:97], v[154:157], v[138:141], v[82:97]
	v_mfma_f32_32x32x16_bf16 v[66:81], v[150:153], v[134:137], v[66:81]
	ds_read_b128 v[138:141], v162 offset:128
	ds_read_b128 v[150:153], v162 offset:12928
	s_waitcnt lgkmcnt(4)
	v_mfma_f32_32x32x16_bf16 v[82:97], v[158:161], v[134:137], v[82:97]
	s_waitcnt lgkmcnt(3)
	v_mfma_f32_32x32x16_bf16 v[66:81], v[142:145], v[130:133], v[66:81]
	ds_read_b128 v[134:137], v162 offset:160
	ds_read_b128 v[142:145], v162 offset:12960
	s_waitcnt lgkmcnt(4)
	v_mfma_f32_32x32x16_bf16 v[82:97], v[146:149], v[130:133], v[82:97]
	s_waitcnt lgkmcnt(3)
	v_mfma_f32_32x32x16_bf16 v[66:81], v[138:141], v[126:129], v[66:81]
	ds_read_b128 v[130:133], v162 offset:192
	ds_read_b128 v[138:141], v162 offset:12992
	s_waitcnt lgkmcnt(4)
	v_mfma_f32_32x32x16_bf16 v[82:97], v[150:153], v[126:129], v[82:97]
	s_waitcnt lgkmcnt(3)
	v_mfma_f32_32x32x16_bf16 v[66:81], v[134:137], v[122:125], v[66:81]
	ds_read_b128 v[126:129], v162 offset:224
	ds_read_b128 v[134:137], v162 offset:13024
	s_waitcnt lgkmcnt(4)
	v_mfma_f32_32x32x16_bf16 v[82:97], v[142:145], v[122:125], v[82:97]
	s_waitcnt lgkmcnt(3)
	v_mfma_f32_32x32x16_bf16 v[66:81], v[130:133], v[118:121], v[66:81]
	ds_read_b128 v[122:125], v162 offset:256
	ds_read_b128 v[130:133], v162 offset:13056
	s_waitcnt lgkmcnt(4)
	v_mfma_f32_32x32x16_bf16 v[82:97], v[138:141], v[118:121], v[82:97]
	s_waitcnt lgkmcnt(3)
	v_mfma_f32_32x32x16_bf16 v[66:81], v[126:129], v[114:117], v[66:81]
	ds_read_b128 v[118:121], v162 offset:288
	ds_read_b128 v[126:129], v162 offset:13088
	s_waitcnt lgkmcnt(4)
	v_mfma_f32_32x32x16_bf16 v[82:97], v[134:137], v[114:117], v[82:97]
	s_waitcnt lgkmcnt(3)
	v_mfma_f32_32x32x16_bf16 v[66:81], v[122:125], v[110:113], v[66:81]
	ds_read_b128 v[114:117], v162 offset:320
	ds_read_b128 v[122:125], v162 offset:13120
	s_waitcnt lgkmcnt(4)
	v_mfma_f32_32x32x16_bf16 v[82:97], v[130:133], v[110:113], v[82:97]
	s_waitcnt lgkmcnt(3)
	v_mfma_f32_32x32x16_bf16 v[66:81], v[118:121], v[106:109], v[66:81]
	ds_read_b128 v[110:113], v162 offset:352
	ds_read_b128 v[118:121], v162 offset:13152
	s_waitcnt lgkmcnt(4)
	v_mfma_f32_32x32x16_bf16 v[82:97], v[126:129], v[106:109], v[82:97]
	s_waitcnt lgkmcnt(3)
	v_mfma_f32_32x32x16_bf16 v[66:81], v[114:117], v[102:105], v[66:81]
	s_waitcnt lgkmcnt(2)
	v_mfma_f32_32x32x16_bf16 v[82:97], v[122:125], v[102:105], v[82:97]
	s_waitcnt lgkmcnt(1)
	v_mfma_f32_32x32x16_bf16 v[66:81], v[110:113], v[98:101], v[66:81]
	v_add_u32_e32 v102, s61, v184
	v_add_u32_e32 v122, v102, v189
	v_add_u32_e32 v115, 0x6000, v122
	v_add_u32_e32 v116, 0x7000, v122
	v_add_u32_e32 v117, 0x8000, v122
	ds_read2_b64 v[102:105], v115 offset0:128 offset1:130
	ds_read2_b64 v[110:113], v116 offset0:160 offset1:162
	s_nop 4
	v_max_f32_e32 v106, v66, v67
	s_waitcnt lgkmcnt(2)
	v_mfma_f32_32x32x16_bf16 v[82:97], v[118:121], v[98:101], v[82:97]
	v_max3_f32 v106, v106, v68, v69
	v_max3_f32 v106, v106, v70, v71
	v_max3_f32 v106, v106, v72, v73
	v_max3_f32 v106, v106, v74, v75
	v_max3_f32 v106, v106, v76, v77
	v_max3_f32 v106, v106, v78, v79
	v_max3_f32 v106, v106, v80, v81
	s_nop 4
	v_max3_f32 v98, v106, v82, v83
	v_max3_f32 v98, v98, v84, v85
	v_max3_f32 v98, v98, v86, v87
	v_max3_f32 v98, v98, v88, v89
	v_max3_f32 v98, v98, v90, v91
	v_max3_f32 v98, v98, v92, v93
	v_max3_f32 v98, v98, v94, v95
	v_max3_f32 v98, v98, v96, v97
	ds_bpermute_b32 v99, v185, v98
	v_add_u32_e32 v118, 0x9000, v122
	ds_read2_b64 v[106:109], v117 offset0:192 offset1:194
	s_waitcnt lgkmcnt(1)
	v_max_f32_e32 v237, v98, v99
	v_cmp_lt_f32_e32 vcc, 0x41000000, v237
	ds_read2_b64 v[98:101], v118 offset0:224 offset1:226
	s_cbranch_vccz .Lfold_1_keep

; #define LAS __attribute__((address_space(3)))
; DI float shfl_xor_l(float v, int lane, int m) { return __int_as_float(__builtin_amdgcn_ds_bpermute((lane ^ m) << 2, __float_as_int(v))); }
; #define A_LOAD(kt) do { const size_t ko = (size_t)(kt) * 64; st0 = *(const u32x4*)(kn_src + ko * 2048); st1 = *(const u32x4*)(kn_src + (ko + 32) * 2048); \
;         st2 = *(const u32x4*)(kr_src + ko * 64); st3 = *(const u32x4*)(v_src + ko); st4 = *(const u32x4*)(v_src + ko + (size_t)64 * 8192); } while (0)
; #define VLD(dst, j, dt) do { LAS unsigned char* va_ = vb + (32 * (dt) + n) * VROW + (16 * (j) + 4 * g) * 2; const u32x2 lo_ = *(const LAS u32x2*)(va_), hi_ = *(const LAS u32x2*)(va_ + 16); dst = (u32x4){lo_.x, lo_.y, hi_.x, hi_.y}; } while (0)
; DI void attn_unit(LAS unsigned char* lds, int wid, int b, int h, int qb) {
;     ...
;     for (int kt = 0; kt < nkt; ++kt) {
;         const int buf = kt & 1;
;         if (kt + 1 < nkt) A_LOAD(kt + 1);
;         if (kt <= cq) {
;             LAS unsigned char* kb = lds + buf * ABUF; LAS unsigned char* vb = kb + KBYTES;
;             f32x16 s0, s1;
; #pragma unroll
;             for (int i = 0; i < 16; ++i) { s0[i] = 0.f; s1[i] = 0.f; }
;     ...
;             bf16x8 ka[3][2];
;             ka[0][0] = KLD(0, 0); ka[0][1] = KLD(0, 1); ka[1][0] = KLD(1, 0); ka[1][1] = KLD(1, 1);
; #pragma unroll
;             for (int ks = 0; ks < 12; ++ks) {
;                 if (ks + 2 < 12) { ka[(ks + 2) % 3][0] = KLD(ks + 2, 0); ka[(ks + 2) % 3][1] = KLD(ks + 2, 1); }
;                 s0 = __builtin_amdgcn_mfma_f32_32x32x16_bf16(ka[ks % 3][0], qf[ks], s0, 0, 0, 0); s1 = __builtin_amdgcn_mfma_f32_32x32x16_bf16(ka[ks % 3][1], qf[ks], s1, 0, 0, 0);
;                 __builtin_amdgcn_sched_barrier(0); }
;             u32x4 vf[2][4];
; #pragma unroll
;             for (int dt = 0; dt < 4; ++dt) VLD(vf[0][dt], 0, dt);
;             float mx = s0[0];
; #pragma unroll
;             for (int i = 1; i < 16; ++i) mx = fmaxf(mx, s0[i]);
; #pragma unroll
;             for (int i = 0; i < 16; ++i) mx = fmaxf(mx, s1[i]);
;             mx = fmaxf(mx, shfl_xor_l(mx, lane, 32));
;             const float mnew = fmaxf(mrow, mx), alpha = __builtin_amdgcn_exp2f(mrow - mnew); mrow = mnew;
.LBB0_1091:
	s_and_b32 s18, s57, 1
	global_load_dwordx4 v[2:5], v198, s[70:71]
	global_load_dwordx4 v[6:9], v198, s[72:73]
	global_load_dwordx4 v[10:13], v196, s[78:79]
	global_load_dwordx4 v[160:163], v194, s[74:75] offset:128
	global_load_dwordx4 v[164:167], v194, s[76:77] offset:128
	s_cmp_gt_u32 s57, s25
	s_cbranch_scc1 .LBB0_1095
	s_mul_i32 s19, s18, 0xa800
	s_add_i32 s19, s19, 0
	v_add3_u32 v0, s19, v193, v204
	ds_read_b128 v[80:83], v0
	ds_read_b128 v[168:171], v0 offset:32
	ds_read_b128 v[96:99], v0 offset:12800
	ds_read_b128 v[174:177], v0 offset:64
	ds_read_b128 v[178:181], v0 offset:12832
	ds_read_b128 v[206:209], v0 offset:12864
	s_waitcnt vmcnt(6) lgkmcnt(3)
	v_mfma_f32_32x32x16_bf16 v[96:111], v[96:99], v[156:159], v[216:231]
	v_mfma_f32_32x32x16_bf16 v[80:95], v[80:83], v[156:159], v[216:231]
	v_mfma_f32_32x32x16_bf16 v[80:95], v[168:171], v[152:155], v[80:95]
	ds_read_b128 v[168:171], v0 offset:96
	ds_read_b128 v[210:213], v0 offset:12896
	s_waitcnt lgkmcnt(3)
	v_mfma_f32_32x32x16_bf16 v[96:111], v[178:181], v[152:155], v[96:111]
	v_mfma_f32_32x32x16_bf16 v[80:95], v[174:177], v[148:151], v[80:95]
	ds_read_b128 v[174:177], v0 offset:128
	ds_read_b128 v[178:181], v0 offset:12928
	s_waitcnt lgkmcnt(4)
	v_mfma_f32_32x32x16_bf16 v[96:111], v[206:209], v[148:151], v[96:111]
	s_waitcnt lgkmcnt(3)
	v_mfma_f32_32x32x16_bf16 v[80:95], v[168:171], v[144:147], v[80:95]
	ds_read_b128 v[168:171], v0 offset:160
	ds_read_b128 v[206:209], v0 offset:12960
	s_waitcnt lgkmcnt(4)
	v_mfma_f32_32x32x16_bf16 v[96:111], v[210:213], v[144:147], v[96:111]
	s_waitcnt lgkmcnt(3)
	v_mfma_f32_32x32x16_bf16 v[80:95], v[174:177], v[140:143], v[80:95]
	ds_read_b128 v[174:177], v0 offset:192
	ds_read_b128 v[210:213], v0 offset:12992
	s_waitcnt lgkmcnt(4)
	v_mfma_f32_32x32x16_bf16 v[96:111], v[178:181], v[140:143], v[96:111]
	s_waitcnt lgkmcnt(3)
	v_mfma_f32_32x32x16_bf16 v[80:95], v[168:171], v[136:139], v[80:95]
	ds_read_b128 v[168:171], v0 offset:224
	ds_read_b128 v[178:181], v0 offset:13024
	s_waitcnt lgkmcnt(4)
	v_mfma_f32_32x32x16_bf16 v[96:111], v[206:209], v[136:139], v[96:111]
	s_waitcnt lgkmcnt(3)
	v_mfma_f32_32x32x16_bf16 v[80:95], v[174:177], v[132:135], v[80:95]
	ds_read_b128 v[174:177], v0 offset:256
	ds_read_b128 v[206:209], v0 offset:13056
	s_waitcnt lgkmcnt(4)
	v_mfma_f32_32x32x16_bf16 v[96:111], v[210:213], v[132:135], v[96:111]
	s_waitcnt lgkmcnt(3)
	v_mfma_f32_32x32x16_bf16 v[80:95], v[168:171], v[128:131], v[80:95]
	ds_read_b128 v[168:171], v0 offset:288
	ds_read_b128 v[210:213], v0 offset:13088
	s_waitcnt lgkmcnt(4)
	v_mfma_f32_32x32x16_bf16 v[96:111], v[178:181], v[128:131], v[96:111]
	s_waitcnt lgkmcnt(3)
	v_mfma_f32_32x32x16_bf16 v[80:95], v[174:177], v[124:127], v[80:95]
	ds_read_b128 v[174:177], v0 offset:320
	ds_read_b128 v[178:181], v0 offset:13120
	s_waitcnt lgkmcnt(4)
	v_mfma_f32_32x32x16_bf16 v[96:111], v[206:209], v[124:127], v[96:111]
	s_waitcnt lgkmcnt(3)
	v_mfma_f32_32x32x16_bf16 v[80:95], v[168:171], v[120:123], v[80:95]
	ds_read_b128 v[168:171], v0 offset:352
	ds_read_b128 v[206:209], v0 offset:13152
	s_waitcnt lgkmcnt(4)
	v_mfma_f32_32x32x16_bf16 v[96:111], v[210:213], v[120:123], v[96:111]
	s_waitcnt lgkmcnt(3)
	v_mfma_f32_32x32x16_bf16 v[80:95], v[174:177], v[116:119], v[80:95]
	s_waitcnt lgkmcnt(2)
	v_mfma_f32_32x32x16_bf16 v[96:111], v[178:181], v[116:119], v[96:111]
	s_waitcnt vmcnt(5) lgkmcnt(1)
	v_mfma_f32_32x32x16_bf16 v[80:95], v[168:171], v[112:115], v[80:95]
	v_add_u32_e32 v0, s19, v188
	v_add_u32_e32 v173, v0, v191
	v_add_u32_e32 v15, 0x6000, v173
	v_add_u32_e32 v205, 0x7000, v173
	ds_read2_b64 v[168:171], v15 offset0:128 offset1:130
	ds_read2_b64 v[180:183], v205 offset0:160 offset1:162
	s_nop 5
	v_max_f32_e32 v0, v80, v81
	s_waitcnt lgkmcnt(2)
	v_mfma_f32_32x32x16_bf16 v[96:111], v[206:209], v[112:115], v[96:111]
	v_max3_f32 v0, v0, v82, v83
	v_max3_f32 v0, v0, v84, v85
	v_max3_f32 v0, v0, v86, v87
	v_max3_f32 v0, v0, v88, v89
	v_max3_f32 v0, v0, v90, v91
	v_max3_f32 v0, v0, v92, v93
	v_max3_f32 v0, v0, v94, v95
	s_nop 4
	v_max3_f32 v0, v0, v96, v97
	v_max3_f32 v0, v0, v98, v99
	v_max3_f32 v0, v0, v100, v101
	v_max3_f32 v0, v0, v102, v103
	v_max3_f32 v0, v0, v104, v105
	v_max3_f32 v0, v0, v106, v107
	v_max3_f32 v0, v0, v108, v109
	v_max3_f32 v0, v0, v110, v111
	ds_bpermute_b32 v14, v189, v0
	v_add_u32_e32 v206, 0x8000, v173
	v_add_u32_e32 v207, 0x9000, v173
	ds_read2_b64 v[176:179], v206 offset0:192 offset1:194
	s_waitcnt lgkmcnt(1)
	v_max_f32_e32 v237, v0, v14
	v_cmp_lt_f32_e32 vcc, 0x41000000, v237
	ds_read2_b64 v[172:175], v207 offset0:224 offset1:226
	s_cmp_eq_u32 s57, 0
	s_cbranch_scc1 .Lfold_2_upd
	s_cbranch_vccz .Lfold_2_keep

; DI void attn_unit(LAS unsigned char* lds, int wid, int b, int h, int qb) {
;     ...
;             const float mnew = fmaxf(mrow, mx), alpha = __builtin_amdgcn_exp2f(mrow - mnew); mrow = mnew;
;             float ls = 0.f;
; #pragma unroll
;             for (int i = 0; i < 16; ++i) { s0[i] = __builtin_amdgcn_exp2f(s0[i] - mnew); s1[i] = __builtin_amdgcn_exp2f(s1[i] - mnew); ls += s0[i] + s1[i]; }
.LBB0_1094:
	v_exp_f32_e32 v80, v80
	v_exp_f32_e32 v96, v96
	v_exp_f32_e32 v81, v81
	v_exp_f32_e32 v97, v97
	v_exp_f32_e32 v82, v82
	v_exp_f32_e32 v98, v98
	v_exp_f32_e32 v83, v83
	v_exp_f32_e32 v99, v99
	v_add_f32_e32 v208, v96, v80
	v_exp_f32_e32 v84, v84
	v_exp_f32_e32 v100, v100

; DI unsigned pk2(float a, float b) { f32x2 f = {a, b}; bf16v2 r = __builtin_convertvector(f, bf16v2); return __builtin_bit_cast(unsigned, r); }
; #define VLD(dst, j, dt) do { LAS unsigned char* va_ = vb + (32 * (dt) + n) * VROW + (16 * (j) + 4 * g) * 2; const u32x2 lo_ = *(const LAS u32x2*)(va_), hi_ = *(const LAS u32x2*)(va_ + 16); dst = (u32x4){lo_.x, lo_.y, hi_.x, hi_.y}; } while (0)
; DI void attn_unit(LAS unsigned char* lds, int wid, int b, int h, int qb) {
;     ...
;             for (int i = 0; i < 16; ++i) { s0[i] = __builtin_amdgcn_exp2f(s0[i] - mnew); s1[i] = __builtin_amdgcn_exp2f(s1[i] - mnew); ls += s0[i] + s1[i]; }
;             lrow = lrow * alpha + ls;
;             if (__builtin_amdgcn_ballot_w64(alpha != 1.f) != 0ull) {
; #pragma unroll
;                 for (int dt = 0; dt < 4; ++dt)
; #pragma unroll
;                     for (int i = 0; i < 16; ++i) o[dt][i] *= alpha;
;             }
;             bf16x8 pf[4];
; #pragma unroll
;             for (int jj = 0; jj < 2; ++jj) { u32x4 w0, w1;
;                 w0.x = pk2(s0[8 * jj + 0], s0[8 * jj + 1]); w0.y = pk2(s0[8 * jj + 2], s0[8 * jj + 3]); w0.z = pk2(s0[8 * jj + 4], s0[8 * jj + 5]); w0.w = pk2(s0[8 * jj + 6], s0[8 * jj + 7]);
;                 w1.x = pk2(s1[8 * jj + 0], s1[8 * jj + 1]); w1.y = pk2(s1[8 * jj + 2], s1[8 * jj + 3]); w1.z = pk2(s1[8 * jj + 4], s1[8 * jj + 5]); w1.w = pk2(s1[8 * jj + 6], s1[8 * jj + 7]);
;                 pf[jj] = __builtin_bit_cast(bf16x8, w0); pf[2 + jj] = __builtin_bit_cast(bf16x8, w1); }
; #pragma unroll
;             for (int j = 0; j < 4; ++j) {
;                 if (j < 3) {
; #pragma unroll
;                     for (int dt = 0; dt < 4; ++dt) VLD(vf[(j + 1) & 1][dt], j + 1, dt);
;                 }
; #pragma unroll
;                 for (int dt = 0; dt < 4; ++dt) o[dt] = __builtin_amdgcn_mfma_f32_32x32x16_bf16(__builtin_bit_cast(bf16x8, vf[j & 1][dt]), pf[j], o[dt], 0, 0, 0);
;                 __builtin_amdgcn_sched_barrier(0); }
;     ...
;         }
;         if (kt + 1 < nkt) A_WRITE(buf ^ 1);
	v_add_f32_e32 v209, v97, v81
	v_exp_f32_e32 v85, v85
	v_exp_f32_e32 v101, v101
	v_add_f32_e32 v208, v209, v208
	v_add_f32_e32 v209, v98, v82
	v_exp_f32_e32 v86, v86
	v_exp_f32_e32 v102, v102
	v_add_f32_e32 v208, v209, v208
	v_add_f32_e32 v209, v99, v83
	v_exp_f32_e32 v87, v87
	v_exp_f32_e32 v103, v103
	v_add_f32_e32 v208, v209, v208
	v_add_f32_e32 v209, v100, v84
	v_exp_f32_e32 v88, v88
	v_exp_f32_e32 v104, v104
	v_add_f32_e32 v208, v209, v208
	v_add_f32_e32 v209, v101, v85
	v_exp_f32_e32 v89, v89
	v_exp_f32_e32 v105, v105
	v_add_f32_e32 v208, v209, v208
	v_add_f32_e32 v209, v102, v86
	v_exp_f32_e32 v90, v90
	v_exp_f32_e32 v106, v106
	v_add_f32_e32 v208, v209, v208
	v_add_f32_e32 v209, v103, v87
	v_exp_f32_e32 v91, v91
	v_exp_f32_e32 v107, v107
	v_add_f32_e32 v208, v209, v208
	v_add_f32_e32 v209, v104, v88
	v_exp_f32_e32 v92, v92
	v_exp_f32_e32 v108, v108
	v_add_f32_e32 v208, v209, v208
	v_add_f32_e32 v209, v105, v89
	v_exp_f32_e32 v93, v93
	v_exp_f32_e32 v109, v109
	v_add_f32_e32 v208, v209, v208
	v_add_f32_e32 v209, v106, v90
	v_exp_f32_e32 v94, v94
	v_exp_f32_e32 v110, v110
	v_add_f32_e32 v208, v209, v208
	v_add_f32_e32 v209, v107, v91
	v_exp_f32_e32 v95, v95
	v_exp_f32_e32 v111, v111
	v_add_f32_e32 v208, v209, v208
	v_add_f32_e32 v209, v108, v92
	v_add_f32_e32 v208, v209, v208
	v_add_f32_e32 v209, v109, v93
	v_add_f32_e32 v208, v209, v208
	v_cvt_pk_bf16_f32 v80, v80, v81
	v_cvt_pk_bf16_f32 v81, v82, v83
	v_cvt_pk_bf16_f32 v82, v84, v85
	v_cvt_pk_bf16_f32 v83, v86, v87
	v_add_f32_e32 v84, v110, v94
	v_add_f32_e32 v84, v84, v208
	v_mfma_f32_32x32x16_bf16 v[64:79], v[168:171], v[80:83], v[64:79]
	v_add_f32_e32 v85, v111, v95
	v_add_f32_e32 v168, v85, v84
	v_cvt_pk_bf16_f32 v84, v96, v97
	v_cvt_pk_bf16_f32 v85, v98, v99
	v_cvt_pk_bf16_f32 v86, v100, v101
	v_cvt_pk_bf16_f32 v87, v102, v103
	v_cvt_pk_bf16_f32 v88, v88, v89
	v_mfma_f32_32x32x16_bf16 v[48:63], v[180:183], v[80:83], v[48:63]
	v_cvt_pk_bf16_f32 v89, v90, v91
	v_cvt_pk_bf16_f32 v90, v92, v93
	v_cvt_pk_bf16_f32 v91, v94, v95
	v_cvt_pk_bf16_f32 v92, v104, v105
	v_cvt_pk_bf16_f32 v93, v106, v107
	v_cvt_pk_bf16_f32 v94, v108, v109
	v_cvt_pk_bf16_f32 v95, v110, v111
	s_waitcnt lgkmcnt(1)
	v_mfma_f32_32x32x16_bf16 v[32:47], v[176:179], v[80:83], v[32:47]
	ds_read2_b64 v[96:99], v15 offset0:132 offset1:134
	ds_read2_b64 v[100:103], v205 offset0:164 offset1:166
	ds_read2_b64 v[104:107], v206 offset0:196 offset1:198
	ds_read2_b64 v[108:111], v207 offset0:228 offset1:230
	v_fma_f32 v185, v185, v0, v168
	s_waitcnt lgkmcnt(4)
	v_mfma_f32_32x32x16_bf16 v[16:31], v[172:175], v[80:83], v[16:31]
	s_waitcnt lgkmcnt(3)
	v_mfma_f32_32x32x16_bf16 v[64:79], v[96:99], v[88:91], v[64:79]
	s_waitcnt lgkmcnt(2)
	v_mfma_f32_32x32x16_bf16 v[48:63], v[100:103], v[88:91], v[48:63]
	s_waitcnt lgkmcnt(1)
	v_mfma_f32_32x32x16_bf16 v[32:47], v[104:107], v[88:91], v[32:47]
	ds_read2_b64 v[80:83], v15 offset0:136 offset1:138
	ds_read2_b64 v[96:99], v205 offset0:168 offset1:170
	ds_read2_b64 v[100:103], v206 offset0:200 offset1:202
	ds_read2_b64 v[104:107], v207 offset0:232 offset1:234
	s_waitcnt lgkmcnt(4)
	v_mfma_f32_32x32x16_bf16 v[16:31], v[108:111], v[88:91], v[16:31]
	s_waitcnt lgkmcnt(3)
	v_mfma_f32_32x32x16_bf16 v[64:79], v[80:83], v[84:87], v[64:79]
	s_waitcnt lgkmcnt(2)
	v_mfma_f32_32x32x16_bf16 v[48:63], v[96:99], v[84:87], v[48:63]
	s_waitcnt lgkmcnt(1)
	v_mfma_f32_32x32x16_bf16 v[32:47], v[100:103], v[84:87], v[32:47]
	ds_read2_b64 v[80:83], v15 offset0:140 offset1:142
	ds_read2_b64 v[88:91], v205 offset0:172 offset1:174
	ds_read2_b64 v[96:99], v206 offset0:204 offset1:206
	ds_read2_b64 v[100:103], v207 offset0:236 offset1:238
	s_waitcnt lgkmcnt(4)
	v_mfma_f32_32x32x16_bf16 v[16:31], v[104:107], v[84:87], v[16:31]
	s_waitcnt lgkmcnt(3)
	v_mfma_f32_32x32x16_bf16 v[64:79], v[80:83], v[92:95], v[64:79]
	s_waitcnt lgkmcnt(2)
	v_mfma_f32_32x32x16_bf16 v[48:63], v[88:91], v[92:95], v[48:63]
	s_waitcnt lgkmcnt(1)
	v_mfma_f32_32x32x16_bf16 v[32:47], v[96:99], v[92:95], v[32:47]
	s_waitcnt lgkmcnt(0)
	v_mfma_f32_32x32x16_bf16 v[16:31], v[100:103], v[92:95], v[16:31]
	s_branch .LBB0_1096
.LBB0_1095:
.LBB0_1096:
	s_add_u32 s70, s70, 0x40000
	s_addc_u32 s71, s71, 0
	s_add_u32 s72, s72, 0x40000
	s_addc_u32 s73, s73, 0
	s_add_u32 s78, s78, 0x2000
	s_addc_u32 s79, s79, 0
	s_add_u32 s74, s74, 0x80
	s_addc_u32 s75, s75, 0
	s_add_u32 s76, s76, 0x80
	s_addc_u32 s77, s77, 0
	s_add_i32 s57, s57, 1
	s_cmp_lg_u32 s18, 0
	s_cbranch_scc1 .Lw2_b0
	s_waitcnt vmcnt(4)
	ds_write_b128 v190, v[2:5] offset:43008
	s_waitcnt vmcnt(3)
	ds_write_b128 v190, v[6:9] offset:55808
	s_waitcnt vmcnt(2)
	ds_write_b128 v192, v[10:13] offset:43264
	s_waitcnt vmcnt(1)
	ds_write2_b64 v240, v[160:161], v[162:163] offset1:1
	s_waitcnt vmcnt(0)
	ds_write2_b64 v241, v[164:165], v[166:167] offset1:1
	s_branch .Lw2_join

; #define LAS __attribute__((address_space(3)))
; DI float shfl_xor_l(float v, int lane, int m) { return __int_as_float(__builtin_amdgcn_ds_bpermute((lane ^ m) << 2, __float_as_int(v))); }
; #define VLD(dst, j, dt) do { LAS unsigned char* va_ = vb + (32 * (dt) + n) * VROW + (16 * (j) + 4 * g) * 2; const u32x2 lo_ = *(const LAS u32x2*)(va_), hi_ = *(const LAS u32x2*)(va_ + 16); dst = (u32x4){lo_.x, lo_.y, hi_.x, hi_.y}; } while (0)
; DI void attn_unit(LAS unsigned char* lds, int wid, int b, int h, int qb) {
;     ...
;         if (kt <= cq) {
;             LAS unsigned char* kb = lds + buf * ABUF; LAS unsigned char* vb = kb + KBYTES;
;             f32x16 s0, s1;
; #pragma unroll
;             for (int i = 0; i < 16; ++i) { s0[i] = 0.f; s1[i] = 0.f; }
;     ...
;             bf16x8 ka[3][2];
;             ka[0][0] = KLD(0, 0); ka[0][1] = KLD(0, 1); ka[1][0] = KLD(1, 0); ka[1][1] = KLD(1, 1);
; #pragma unroll
;             for (int ks = 0; ks < 12; ++ks) {
;                 if (ks + 2 < 12) { ka[(ks + 2) % 3][0] = KLD(ks + 2, 0); ka[(ks + 2) % 3][1] = KLD(ks + 2, 1); }
;                 s0 = __builtin_amdgcn_mfma_f32_32x32x16_bf16(ka[ks % 3][0], qf[ks], s0, 0, 0, 0); s1 = __builtin_amdgcn_mfma_f32_32x32x16_bf16(ka[ks % 3][1], qf[ks], s1, 0, 0, 0);
;                 __builtin_amdgcn_sched_barrier(0); }
;             u32x4 vf[2][4];
; #pragma unroll
;             for (int dt = 0; dt < 4; ++dt) VLD(vf[0][dt], 0, dt);
;             float mx = s0[0];
; #pragma unroll
;             for (int i = 1; i < 16; ++i) mx = fmaxf(mx, s0[i]);
; #pragma unroll
;             for (int i = 0; i < 16; ++i) mx = fmaxf(mx, s1[i]);
;             mx = fmaxf(mx, shfl_xor_l(mx, lane, 32));
;             const float mnew = fmaxf(mrow, mx), alpha = __builtin_amdgcn_exp2f(mrow - mnew); mrow = mnew;
;     ...
;         if (kt + 1 < nkt) A_WRITE(buf ^ 1);
;         __syncthreads();
.Lw2_join:
	s_cmp_eq_u32 s4, s57
	s_waitcnt lgkmcnt(0)
	s_barrier
	s_cbranch_scc1 .LBB0_1098
	s_branch .LBB0_1091
.LBB0_1098:
	s_lshl_b32 s18, s56, 2
	s_or_b32 s18, s18, 2
	s_cmp_ge_u32 s18, s25
	s_cbranch_scc1 .LBB0_1077
	s_bitcmp1_b32 s4, 0
	s_cselect_b32 s4, 0xa800, 0
	s_add_i32 s4, s4, 0
	v_add3_u32 v0, s4, v193, v204
	ds_read_b128 v[2:5], v0
	ds_read_b128 v[6:9], v0 offset:32
	s_waitcnt lgkmcnt(1)
	v_mfma_f32_32x32x16_bf16 v[80:95], v[2:5], v[156:159], v[216:231]
	ds_read_b128 v[2:5], v0 offset:12800
	ds_read_b128 v[10:13], v0 offset:64
	ds_read_b128 v[160:163], v0 offset:12832
	ds_read_b128 v[164:167], v0 offset:12864
	s_waitcnt lgkmcnt(3)
	v_mfma_f32_32x32x16_bf16 v[96:111], v[2:5], v[156:159], v[216:231]
	v_mfma_f32_32x32x16_bf16 v[80:95], v[6:9], v[152:155], v[80:95]
	ds_read_b128 v[2:5], v0 offset:96
	ds_read_b128 v[6:9], v0 offset:12896
	s_waitcnt lgkmcnt(3)
	v_mfma_f32_32x32x16_bf16 v[96:111], v[160:163], v[152:155], v[96:111]
	v_mfma_f32_32x32x16_bf16 v[80:95], v[10:13], v[148:151], v[80:95]
	ds_read_b128 v[10:13], v0 offset:128
	ds_read_b128 v[152:155], v0 offset:12928
	s_waitcnt lgkmcnt(4)
	v_mfma_f32_32x32x16_bf16 v[96:111], v[164:167], v[148:151], v[96:111]
	s_waitcnt lgkmcnt(3)
	v_mfma_f32_32x32x16_bf16 v[80:95], v[2:5], v[144:147], v[80:95]
	ds_read_b128 v[2:5], v0 offset:160
	ds_read_b128 v[148:151], v0 offset:12960
	s_waitcnt lgkmcnt(4)
	v_mfma_f32_32x32x16_bf16 v[96:111], v[6:9], v[144:147], v[96:111]
	s_waitcnt lgkmcnt(3)
	v_mfma_f32_32x32x16_bf16 v[80:95], v[10:13], v[140:143], v[80:95]
	ds_read_b128 v[6:9], v0 offset:192
	ds_read_b128 v[10:13], v0 offset:12992
	s_waitcnt lgkmcnt(4)
	v_mfma_f32_32x32x16_bf16 v[96:111], v[152:155], v[140:143], v[96:111]
	s_waitcnt lgkmcnt(3)
	v_mfma_f32_32x32x16_bf16 v[80:95], v[2:5], v[136:139], v[80:95]
	ds_read_b128 v[2:5], v0 offset:224
	ds_read_b128 v[140:143], v0 offset:13024
	s_waitcnt lgkmcnt(4)
	v_mfma_f32_32x32x16_bf16 v[96:111], v[148:151], v[136:139], v[96:111]
	s_waitcnt lgkmcnt(3)
	v_mfma_f32_32x32x16_bf16 v[80:95], v[6:9], v[132:135], v[80:95]
	ds_read_b128 v[6:9], v0 offset:256
	ds_read_b128 v[136:139], v0 offset:13056
	s_waitcnt lgkmcnt(4)
	v_mfma_f32_32x32x16_bf16 v[96:111], v[10:13], v[132:135], v[96:111]
	s_waitcnt lgkmcnt(3)
	v_mfma_f32_32x32x16_bf16 v[80:95], v[2:5], v[128:131], v[80:95]
	ds_read_b128 v[2:5], v0 offset:288
	ds_read_b128 v[10:13], v0 offset:13088
	s_waitcnt lgkmcnt(4)
	v_mfma_f32_32x32x16_bf16 v[96:111], v[140:143], v[128:131], v[96:111]
	s_waitcnt lgkmcnt(3)
	v_mfma_f32_32x32x16_bf16 v[80:95], v[6:9], v[124:127], v[80:95]
	ds_read_b128 v[6:9], v0 offset:320
	ds_read_b128 v[128:131], v0 offset:13120
	s_waitcnt lgkmcnt(4)
	v_mfma_f32_32x32x16_bf16 v[96:111], v[136:139], v[124:127], v[96:111]
	s_waitcnt lgkmcnt(3)
	v_mfma_f32_32x32x16_bf16 v[80:95], v[2:5], v[120:123], v[80:95]
	ds_read_b128 v[2:5], v0 offset:352
	ds_read_b128 v[124:127], v0 offset:13152
	s_waitcnt lgkmcnt(4)
	v_mfma_f32_32x32x16_bf16 v[96:111], v[10:13], v[120:123], v[96:111]
	s_waitcnt lgkmcnt(3)
	v_mfma_f32_32x32x16_bf16 v[80:95], v[6:9], v[116:119], v[80:95]
	s_waitcnt lgkmcnt(2)
	v_mfma_f32_32x32x16_bf16 v[96:111], v[128:131], v[116:119], v[96:111]
	s_waitcnt lgkmcnt(1)
	v_mfma_f32_32x32x16_bf16 v[80:95], v[2:5], v[112:115], v[80:95]
	v_add_u32_e32 v0, s4, v188
	v_add_u32_e32 v6, v0, v191
	v_add_u32_e32 v15, 0x6000, v6
	v_add_u32_e32 v116, 0x7000, v6
	v_add_u32_e32 v117, 0x8000, v6
	ds_read2_b64 v[2:5], v15 offset0:128 offset1:130
	ds_read2_b64 v[10:13], v117 offset0:192 offset1:194
	s_nop 4
	v_max_f32_e32 v0, v80, v81
	s_waitcnt lgkmcnt(2)
	v_mfma_f32_32x32x16_bf16 v[96:111], v[124:127], v[112:115], v[96:111]
	v_max3_f32 v0, v0, v82, v83
	v_max3_f32 v0, v0, v84, v85
	v_max3_f32 v0, v0, v86, v87
	v_max3_f32 v0, v0, v88, v89
	v_max3_f32 v0, v0, v90, v91
	v_max3_f32 v0, v0, v92, v93
	v_max3_f32 v0, v0, v94, v95
	s_nop 4
	v_max3_f32 v0, v0, v96, v97
	v_max3_f32 v0, v0, v98, v99
	v_max3_f32 v0, v0, v100, v101
	v_max3_f32 v0, v0, v102, v103
	v_max3_f32 v0, v0, v104, v105
	v_max3_f32 v0, v0, v106, v107
	v_max3_f32 v0, v0, v108, v109
	v_max3_f32 v0, v0, v110, v111
	ds_bpermute_b32 v7, v189, v0
	ds_read2_b64 v[112:115], v116 offset0:160 offset1:162
	s_waitcnt lgkmcnt(1)
	v_max_f32_e32 v237, v0, v7
	v_add_u32_e32 v14, 0x9000, v6
	v_cmp_lt_f32_e32 vcc, 0x41000000, v237
	ds_read2_b64 v[6:9], v14 offset0:224 offset1:226
	s_cbranch_vccz .Lfold_3_keep
